# stack: zero-fill hoist + scheduling header ahead of the prologue barrier + row-pass pre-loop loads issued back to back
# speedup vs baseline: 1.0079x; 1.0005x over previous
.LBB0_323:
	s_add_i32 m0, s9, 0x18000
	v_lshl_add_u64 v[8:9], v[8:9], 0, s[12:13]
	s_waitcnt vmcnt(2)
	s_barrier
	global_load_lds_dwordx4 v[8:9], off
	v_lshl_add_u64 v[4:5], v[4:5], 0, s[12:13]
	s_add_i32 m0, s9, 0x1a000
	s_add_i32 s77, s9, 0x8000
	global_load_lds_dwordx4 v[4:5], off
	v_lshl_add_u64 v[4:5], v[6:7], 0, s[12:13]
	s_mov_b32 m0, s77
	s_add_i32 s86, s9, 0xa000
	global_load_lds_dwordx4 v[4:5], off
	v_lshl_add_u64 v[4:5], v[10:11], 0, s[12:13]
	s_mov_b32 m0, s86
	v_lshl_add_u64 v[2:3], v[2:3], 0, s[12:13]
	global_load_lds_dwordx4 v[4:5], off
	s_add_i32 m0, s9, 0x1c000
	v_lshl_add_u64 v[0:1], v[0:1], 0, s[12:13]
	global_load_lds_dwordx4 v[2:3], off
	s_add_i32 m0, s9, 0x1e000
	s_and_b32 s48, s0, 3
	global_load_lds_dwordx4 v[0:1], off
	v_bfe_u32 v0, v12, 4, 2
	v_and_b32_e32 v1, 15, v12
	v_lshlrev_b32_e32 v3, 4, v0
	v_lshl_or_b32 v146, s1, 6, v1
	v_lshl_or_b32 v1, v1, 6, v3
	v_lshlrev_b32_e32 v3, 2, v12
	s_lshr_b32 s64, s52, 6
	s_lshl_b32 s0, s1, 13
	v_and_b32_e32 v3, 32, v3
	v_bitop3_b32 v4, v1, s0, v3 bitop3:0xde
	s_lshl_b32 s0, s48, 12
	s_add_i32 s87, s64, -2
	s_cmpk_lt_u32 s38, 0x100
	v_bitop3_b32 v147, v1, s0, v3 bitop3:0xde
	s_cselect_b64 s[0:1], -1, 0
	s_lshl_b32 s65, s50, 2
	v_cvt_f32_u32_e32 v1, s65
	v_lshlrev_b32_e32 v2, 3, v0
	v_writelane_b32 v233, s0, 50
	v_cmp_eq_u32_e64 s[38:39], 0, v0
	v_rcp_iflag_f32_e32 v0, v1
	v_writelane_b32 v233, s1, 51
	s_mov_b32 s0, s54
	s_mov_b32 s1, s47
	s_mov_b64 s[62:63], s[0:1]
	v_readlane_b32 s0, v233, 58
	s_lshr_b32 s61, s54, 3
	v_readlane_b32 s1, v233, 59
	s_and_b64 s[0:1], s[0:1], exec
	v_mul_f32_e32 v0, 0x4f7ffffe, v0
	v_readlane_b32 s0, v232, 2
	v_readlane_b32 s40, v233, 56
	v_cvt_u32_f32_e32 v0, v0
	v_readlane_b32 s1, v232, 3
	v_readlane_b32 s41, v233, 57
	s_cselect_b32 s1, s41, s1
	s_cselect_b32 s0, s40, s0
	v_writelane_b32 v232, s0, 8
	v_mov_b32_e32 v1, v97
	s_mov_b32 s66, 0
	v_writelane_b32 v232, s1, 9
	v_readfirstlane_b32 s1, v0
	v_add_u32_e32 v0, v15, v13
	s_sub_i32 s0, 0, s65
	v_add_lshl_u32 v0, v0, v14, 1
	s_mul_i32 s0, s0, s1
	v_lshl_add_u64 v[136:137], s[34:35], 0, v[0:1]
	v_add_u32_e32 v0, v18, v16
	s_mul_hi_u32 s0, s1, s0
	v_add_lshl_u32 v0, v0, v17, 1
	s_mov_b32 s60, s48
	v_lshl_or_b32 v148, s48, 5, v2
	s_add_i32 s68, s1, s0
	v_lshl_add_u64 v[138:139], s[34:35], 0, v[0:1]
	v_add_u32_e32 v149, 0, v4
	s_mov_b32 s51, 0
	v_writelane_b32 v232, s51, 60
	s_branch .LBB0_326

.LBB0_332:
	s_add_u32 s42, s42, 0x80
	s_addc_u32 s43, s43, 0
	s_add_u32 s48, s78, 0x100
	s_addc_u32 s49, s79, 0
	s_mov_b32 s50, 0
	v_readlane_b32 s51, v232, 60
	s_cmp_eq_u32 s51, 0
	s_cbranch_scc0 .Lk_peel
	v_mov_b32_e32 v0, 0
	v_mov_b32_e32 v1, v0
	v_mov_b32_e32 v2, v0
	v_mov_b32_e32 v3, v0
	v_mov_b32_e32 v4, v0
	v_mov_b32_e32 v5, v0
	v_mov_b32_e32 v6, v0
	v_mov_b32_e32 v7, v0
	v_mov_b32_e32 v16, v0
	v_mov_b32_e32 v17, v0
	v_mov_b32_e32 v18, v0
	v_mov_b32_e32 v8, v0
	v_mov_b32_e32 v9, v0
	v_mov_b32_e32 v10, v0
	v_mov_b32_e32 v11, v0
	v_mov_b32_e32 v12, v0
	v_mov_b32_e32 v13, v0
	v_mov_b32_e32 v14, v0
	v_mov_b32_e32 v15, v0
	s_waitcnt vmcnt(6)
	s_barrier

.LBB0_490:
	v_mov_b32_e32 v80, 0
	v_mov_b32_e32 v99, 0
	s_andn2_b64 vcc, exec, s[40:41]
	v_lshlrev_b32_e32 v96, 3, v159
	v_mov_b32_e32 v60, 0
	v_mov_b32_e32 v81, 0
	v_mov_b32_e32 v78, 0
	v_mov_b32_e32 v79, 0
	v_mov_b32_e32 v74, 0
	v_mov_b32_e32 v75, 0
	v_mov_b32_e32 v72, 0
	v_mov_b32_e32 v73, 0
	s_cbranch_vccnz .LBB0_492
	s_lshl_b64 s[0:1], s[8:9], 11
	v_readlane_b32 s40, v236, 10
	v_readlane_b32 s41, v236, 11
	s_add_u32 s40, s40, s0
	s_addc_u32 s41, s41, s1
	s_nop 2
	global_load_dwordx2 v[80:81], v96, s[40:41]
	global_load_dwordx2 v[78:79], v96, s[40:41] offset:512
	global_load_dwordx2 v[74:75], v96, s[40:41] offset:1024
	global_load_dwordx2 v[72:73], v96, s[40:41] offset:1536
	s_lshl_b64 s[40:41], s[8:9], 2
	v_readlane_b32 s42, v235, 22
	s_add_u32 s40, s42, s40
	v_readlane_b32 s42, v235, 23
	s_addc_u32 s41, s42, s41
	global_load_dword v60, v97, s[40:41]
	v_mov_b32_e32 v16, 0
	v_mov_b32_e32 v17, v16
	v_mov_b32_e32 v18, v16
	v_mov_b32_e32 v19, v16
	v_mov_b32_e32 v24, v16
	v_mov_b32_e32 v25, v16
	v_mov_b32_e32 v26, v16
	v_mov_b32_e32 v27, v16
	v_mov_b32_e32 v36, v16
	v_mov_b32_e32 v37, v16
	v_mov_b32_e32 v38, v16
	v_mov_b32_e32 v39, v16
	v_mov_b32_e32 v44, v16
	v_mov_b32_e32 v45, v16
	v_mov_b32_e32 v46, v16
	v_mov_b32_e32 v47, v16
